# modulation GEMV items: L2 prefetch of the later k-iterations' w_mod rows
# baseline (speedup 1.0000x reference)
.LBB0_718:
	s_or_b64 exec, exec, s[6:7]
	s_mul_hi_i32 s6, s12, 0x2aaaaaab
	s_lshr_b32 s7, s6, 31
	s_ashr_i32 s6, s6, 4
	s_add_i32 s6, s6, s7
	s_mul_i32 s7, s6, 0x60
	v_ashrrev_i32_e32 v67, 4, v66
	s_sub_i32 s10, s12, s7
	s_ashr_i32 s7, s6, 31
	v_lshlrev_b32_e32 v2, 5, v67
	s_lshl_b64 s[8:9], s[6:7], 10
	v_ashrrev_i32_e32 v3, 31, v2
	v_lshl_add_u64 v[2:3], s[8:9], 0, v[2:3]
	v_mov_b64_e32 v[6:7], s[62:63]
	v_mad_u64_u32 v[6:7], s[8:9], v2, s29, v[6:7]
	s_lshl_b32 s8, s10, 6
	v_mad_i32_i24 v7, v3, s29, v7
	s_ashr_i32 s9, s8, 31
	v_and_b32_e32 v4, 60, v4
	v_lshl_add_u64 v[2:3], s[8:9], 2, v[6:7]
	v_lshlrev_b32_e32 v162, 2, v4
	v_lshl_add_u64 v[62:63], v[2:3], 0, v[162:163]
	v_add_co_u32_e32 v166, vcc, 0x30000, v62
	v_addc_co_u32_e32 v167, vcc, 0, v63, vcc
	global_load_dwordx4 v[120:123], v[166:167], off
	v_add_co_u32_e32 v166, vcc, 0x36000, v62
	v_addc_co_u32_e32 v167, vcc, 0, v63, vcc
	global_load_dwordx4 v[124:127], v[166:167], off
	v_add_co_u32_e32 v166, vcc, 0x3c000, v62
	v_addc_co_u32_e32 v167, vcc, 0, v63, vcc
	global_load_dwordx4 v[128:131], v[166:167], off
	v_add_co_u32_e32 v166, vcc, 0x42000, v62
	v_addc_co_u32_e32 v167, vcc, 0, v63, vcc
	global_load_dwordx4 v[132:135], v[166:167], off
	v_add_co_u32_e32 v166, vcc, 0x48000, v62
	v_addc_co_u32_e32 v167, vcc, 0, v63, vcc
	global_load_dwordx4 v[136:139], v[166:167], off
	v_add_co_u32_e32 v166, vcc, 0x4e000, v62
	v_addc_co_u32_e32 v167, vcc, 0, v63, vcc
	global_load_dwordx4 v[140:143], v[166:167], off
	v_add_co_u32_e32 v166, vcc, 0x54000, v62
	v_addc_co_u32_e32 v167, vcc, 0, v63, vcc
	global_load_dwordx4 v[144:147], v[166:167], off
	v_add_co_u32_e32 v166, vcc, 0x5a000, v62
	v_addc_co_u32_e32 v167, vcc, 0, v63, vcc
	global_load_dwordx4 v[148:151], v[166:167], off
	v_add_co_u32_e32 v166, vcc, 0x60000, v62
	v_addc_co_u32_e32 v167, vcc, 0, v63, vcc
	global_load_dwordx4 v[152:155], v[166:167], off
	v_add_co_u32_e32 v166, vcc, 0x66000, v62
	v_addc_co_u32_e32 v167, vcc, 0, v63, vcc
	global_load_dwordx4 v[156:159], v[166:167], off
	v_add_co_u32_e32 v166, vcc, 0x6c000, v62
	v_addc_co_u32_e32 v167, vcc, 0, v63, vcc
	global_load_dwordx4 v[212:215], v[166:167], off
	v_add_co_u32_e32 v166, vcc, 0x72000, v62
	v_addc_co_u32_e32 v167, vcc, 0, v63, vcc
	global_load_dwordx4 v[216:219], v[166:167], off
	v_add_co_u32_e32 v166, vcc, 0x78000, v62
	v_addc_co_u32_e32 v167, vcc, 0, v63, vcc
	global_load_dwordx4 v[220:223], v[166:167], off
	v_add_co_u32_e32 v166, vcc, 0x7e000, v62
	v_addc_co_u32_e32 v167, vcc, 0, v63, vcc
	global_load_dwordx4 v[224:227], v[166:167], off
	v_add_co_u32_e32 v166, vcc, 0x84000, v62
	v_addc_co_u32_e32 v167, vcc, 0, v63, vcc
	global_load_dwordx4 v[228:231], v[166:167], off
	v_add_co_u32_e32 v166, vcc, 0x8a000, v62
	v_addc_co_u32_e32 v167, vcc, 0, v63, vcc
	global_load_dwordx4 v[232:235], v[166:167], off
	v_add_co_u32_e32 v166, vcc, 0x90000, v62
	v_addc_co_u32_e32 v167, vcc, 0, v63, vcc
	global_load_dwordx4 v[236:239], v[166:167], off
	v_add_co_u32_e32 v166, vcc, 0x96000, v62
	v_addc_co_u32_e32 v167, vcc, 0, v63, vcc
	global_load_dwordx4 v[240:243], v[166:167], off
	v_add_co_u32_e32 v166, vcc, 0x9c000, v62
	v_addc_co_u32_e32 v167, vcc, 0, v63, vcc
	global_load_dwordx4 v[244:247], v[166:167], off
	v_add_co_u32_e32 v166, vcc, 0xa2000, v62
	v_addc_co_u32_e32 v167, vcc, 0, v63, vcc
	global_load_dwordx4 v[248:251], v[166:167], off
	v_add_co_u32_e32 v166, vcc, 0xa8000, v62
	v_addc_co_u32_e32 v167, vcc, 0, v63, vcc
	global_load_dwordx4 v[174:177], v[166:167], off
	v_add_co_u32_e32 v166, vcc, 0xae000, v62
	v_addc_co_u32_e32 v167, vcc, 0, v63, vcc
	global_load_dwordx4 v[178:181], v[166:167], off
	v_add_co_u32_e32 v166, vcc, 0xb4000, v62
	v_addc_co_u32_e32 v167, vcc, 0, v63, vcc
	global_load_dwordx4 v[182:185], v[166:167], off
	v_add_co_u32_e32 v166, vcc, 0xba000, v62
	v_addc_co_u32_e32 v167, vcc, 0, v63, vcc
	global_load_dwordx4 v[186:189], v[166:167], off
	v_mov_b32_e32 v2, 0
	s_waitcnt vmcnt(14)
	v_lshl_add_u32 v68, v67, 7, 0
	s_mov_b64 s[10:11], 0
	v_mov_b32_e32 v3, v2
	v_mov_b32_e32 v4, v2
	v_mov_b32_e32 v5, v2
	v_mov_b32_e32 v6, v2
	v_mov_b32_e32 v7, v2
	v_mov_b32_e32 v8, v2
	v_mov_b32_e32 v9, v2
	v_mov_b32_e32 v10, v2
	v_mov_b32_e32 v11, v2
	v_mov_b32_e32 v12, v2
	v_mov_b32_e32 v13, v2
	v_mov_b32_e32 v14, v2
	v_mov_b32_e32 v15, v2
	v_mov_b32_e32 v16, v2
	v_mov_b32_e32 v17, v2
	v_mov_b32_e32 v18, v2
	v_mov_b32_e32 v19, v2
	v_mov_b32_e32 v20, v2
	v_mov_b32_e32 v21, v2
	s_waitcnt lgkmcnt(0)
	s_barrier
